# P3 epilogue: X1B stores sc1 (write-through), plus x loads nt
# speedup vs baseline: 1.0338x; 1.0332x over previous
.LBB0_385:
	v_mov_b32_e32 v140, v144
	s_lshl_b32 s9, s44, 8
	v_readfirstlane_b32 s8, v140
	s_bfe_u32 s29, s8, 0x20006
	s_ashr_i32 s8, s8, 2
	s_andn2_b32 s8, s8, 63
	s_add_i32 s8, s8, s9
	v_and_or_b32 v142, v140, 15, s8
	s_lshl_b32 s8, s20, 8
	s_lshl_b32 s9, s29, 6
	v_bfe_u32 v149, v140, 4, 2
	s_or_b32 s8, s9, s8
	v_lshl_or_b32 v140, v149, 3, s8
	v_ashrrev_i32_e32 v143, 31, v142
	v_ashrrev_i32_e32 v141, 31, v140
	v_lshlrev_b64 v[150:151], 10, v[142:143]
	v_lshl_add_u64 v[158:159], v[150:151], 0, v[140:141]
	v_lshl_add_u64 v[160:161], v[158:159], 2, s[12:13]
	global_load_dwordx4 v[150:153], v[160:161], off nt
	global_load_dwordx4 v[154:157], v[160:161], off offset:16 nt
	v_lshl_add_u64 v[158:159], v[158:159], 1, s[16:17]
	s_lshl_b32 s44, s20, 2
	v_cmp_eq_u32_e32 vcc, 0, v149
	s_ashr_i32 s45, s44, 31
	s_waitcnt vmcnt(0)
	v_pk_add_f32 v[152:153], v[126:127], v[152:153]
	v_pk_add_f32 v[150:151], v[124:125], v[150:151]
	v_pk_add_f32 v[156:157], v[122:123], v[156:157]
	v_pk_add_f32 v[154:155], v[120:121], v[154:155]
	v_cvt_pk_bf16_f32 v120, v150, v151
	v_cvt_pk_bf16_f32 v121, v152, v153
	v_cvt_pk_bf16_f32 v122, v154, v155
	v_cvt_pk_bf16_f32 v123, v156, v157
	global_store_dwordx4 v[158:159], v[120:123], off sc1
	global_load_dwordx4 v[120:123], v[160:161], off offset:128 nt
	s_nop 0
	global_load_dwordx4 v[124:127], v[160:161], off offset:144 nt
	v_mul_f32_e32 v151, v151, v151
	v_mul_f32_e32 v153, v153, v153
	v_mul_f32_e32 v155, v155, v155
	v_mul_f32_e32 v157, v157, v157
	v_fmac_f32_e32 v151, v150, v150
	v_fmac_f32_e32 v153, v152, v152
	v_fmac_f32_e32 v155, v154, v154
	v_fmac_f32_e32 v157, v156, v156
	v_add_f32_e32 v150, v151, v153
	v_add_f32_e32 v151, v155, v157
	v_add_f32_e32 v150, v150, v151
	s_waitcnt vmcnt(1)
	v_pk_add_f32 v[118:119], v[118:119], v[122:123]
	v_pk_add_f32 v[116:117], v[116:117], v[120:121]
	s_waitcnt vmcnt(0)
	v_pk_add_f32 v[120:121], v[114:115], v[126:127]
	v_pk_add_f32 v[122:123], v[112:113], v[124:125]
	v_mul_f32_e32 v112, v117, v117
	v_mul_f32_e32 v113, v119, v119
	v_mul_f32_e32 v114, v123, v123
	v_mul_f32_e32 v115, v121, v121
	v_fmac_f32_e32 v112, v116, v116
	v_fmac_f32_e32 v113, v118, v118
	v_fmac_f32_e32 v114, v122, v122
	v_fmac_f32_e32 v115, v120, v120
	v_add_f32_e32 v112, v112, v113
	v_add_f32_e32 v113, v114, v115
	v_add_f32_e32 v112, v112, v113
	v_add_f32_e32 v112, v150, v112
	ds_bpermute_b32 v113, v193, v112
	v_cvt_pk_bf16_f32 v114, v116, v117
	v_cvt_pk_bf16_f32 v115, v118, v119
	v_cvt_pk_bf16_f32 v116, v122, v123
	v_cvt_pk_bf16_f32 v117, v120, v121
	s_waitcnt lgkmcnt(0)
	v_add_f32_e32 v112, v112, v113
	ds_bpermute_b32 v113, v194, v112
	global_store_dwordx4 v[158:159], v[114:117], off offset:64 sc1
	s_and_saveexec_b64 s[46:47], vcc
	s_cbranch_execz .LBB0_387
	v_lshlrev_b64 v[114:115], 6, v[142:143]
	v_lshl_add_u64 v[114:115], s[6:7], 0, v[114:115]
	v_lshl_add_u64 v[114:115], s[44:45], 2, v[114:115]
	s_lshl_b32 s20, s29, 2
	v_lshl_add_u64 v[114:115], v[114:115], 0, s[20:21]
	s_waitcnt lgkmcnt(0)
	v_add_f32_e32 v112, v112, v113
	global_store_dword v[114:115], v112, off
.LBB0_387:
	s_or_b64 exec, exec, s[46:47]
	v_or_b32_e32 v112, 16, v142
	s_waitcnt lgkmcnt(0)
	v_ashrrev_i32_e32 v113, 31, v112
	v_lshlrev_b64 v[114:115], 10, v[112:113]
	v_lshl_add_u64 v[122:123], v[114:115], 0, v[140:141]
	v_lshl_add_u64 v[124:125], v[122:123], 2, s[12:13]
	global_load_dwordx4 v[114:117], v[124:125], off nt
	global_load_dwordx4 v[118:121], v[124:125], off offset:16 nt
	v_lshl_add_u64 v[122:123], v[122:123], 1, s[16:17]
	s_waitcnt vmcnt(1)
	v_pk_add_f32 v[116:117], v[110:111], v[116:117]
	v_pk_add_f32 v[114:115], v[108:109], v[114:115]
	s_waitcnt vmcnt(0)
	v_pk_add_f32 v[120:121], v[106:107], v[120:121]
	v_pk_add_f32 v[118:119], v[104:105], v[118:119]
	v_cvt_pk_bf16_f32 v104, v114, v115
	v_cvt_pk_bf16_f32 v105, v116, v117
	v_cvt_pk_bf16_f32 v106, v118, v119
	v_cvt_pk_bf16_f32 v107, v120, v121
	global_store_dwordx4 v[122:123], v[104:107], off sc1
	global_load_dwordx4 v[104:107], v[124:125], off offset:128 nt
	s_nop 0
	global_load_dwordx4 v[108:111], v[124:125], off offset:144 nt
	v_mul_f32_e32 v115, v115, v115
	v_mul_f32_e32 v117, v117, v117
	v_mul_f32_e32 v119, v119, v119
	v_mul_f32_e32 v121, v121, v121
	v_fmac_f32_e32 v115, v114, v114
	v_fmac_f32_e32 v117, v116, v116
	v_fmac_f32_e32 v119, v118, v118
	v_fmac_f32_e32 v121, v120, v120
	v_add_f32_e32 v114, v115, v117
	v_add_f32_e32 v115, v119, v121
	v_add_f32_e32 v114, v114, v115
	s_waitcnt vmcnt(1)
	v_pk_add_f32 v[102:103], v[102:103], v[106:107]
	v_pk_add_f32 v[100:101], v[100:101], v[104:105]
	s_waitcnt vmcnt(0)
	v_pk_add_f32 v[104:105], v[98:99], v[110:111]
	v_pk_add_f32 v[106:107], v[96:97], v[108:109]
	v_mul_f32_e32 v96, v101, v101
	v_mul_f32_e32 v97, v103, v103
	v_mul_f32_e32 v98, v107, v107
	v_mul_f32_e32 v99, v105, v105
	v_fmac_f32_e32 v96, v100, v100
	v_fmac_f32_e32 v97, v102, v102
	v_fmac_f32_e32 v98, v106, v106
	v_fmac_f32_e32 v99, v104, v104
	v_add_f32_e32 v96, v96, v97
	v_add_f32_e32 v97, v98, v99
	v_add_f32_e32 v96, v96, v97
	v_add_f32_e32 v96, v114, v96
	ds_bpermute_b32 v97, v193, v96
	v_cvt_pk_bf16_f32 v98, v100, v101
	v_cvt_pk_bf16_f32 v99, v102, v103
	v_cvt_pk_bf16_f32 v100, v106, v107
	v_cvt_pk_bf16_f32 v101, v104, v105
	s_waitcnt lgkmcnt(0)
	v_add_f32_e32 v96, v96, v97
	ds_bpermute_b32 v97, v194, v96
	global_store_dwordx4 v[122:123], v[98:101], off offset:64 sc1
	s_and_saveexec_b64 s[46:47], vcc
	s_cbranch_execz .LBB0_389
	v_lshlrev_b64 v[98:99], 6, v[112:113]
	v_lshl_add_u64 v[98:99], s[6:7], 0, v[98:99]
	v_lshl_add_u64 v[98:99], s[44:45], 2, v[98:99]
	s_lshl_b32 s20, s29, 2
	v_lshl_add_u64 v[98:99], v[98:99], 0, s[20:21]
	s_waitcnt lgkmcnt(0)
	v_add_f32_e32 v96, v96, v97
	global_store_dword v[98:99], v96, off
.LBB0_389:
	s_or_b64 exec, exec, s[46:47]
	v_or_b32_e32 v96, 32, v142
	s_waitcnt lgkmcnt(0)
	v_ashrrev_i32_e32 v97, 31, v96
	v_lshlrev_b64 v[98:99], 10, v[96:97]
	v_lshl_add_u64 v[106:107], v[98:99], 0, v[140:141]
	v_lshl_add_u64 v[108:109], v[106:107], 2, s[12:13]
	global_load_dwordx4 v[98:101], v[108:109], off nt
	global_load_dwordx4 v[102:105], v[108:109], off offset:16 nt
	v_lshl_add_u64 v[106:107], v[106:107], 1, s[16:17]
	s_waitcnt vmcnt(1)
	v_pk_add_f32 v[100:101], v[94:95], v[100:101]
	v_pk_add_f32 v[98:99], v[92:93], v[98:99]
	s_waitcnt vmcnt(0)
	v_pk_add_f32 v[104:105], v[90:91], v[104:105]
	v_pk_add_f32 v[102:103], v[88:89], v[102:103]
	v_cvt_pk_bf16_f32 v88, v98, v99
	v_cvt_pk_bf16_f32 v89, v100, v101
	v_cvt_pk_bf16_f32 v90, v102, v103
	v_cvt_pk_bf16_f32 v91, v104, v105
	global_store_dwordx4 v[106:107], v[88:91], off sc1
	global_load_dwordx4 v[88:91], v[108:109], off offset:128 nt
	s_nop 0
	global_load_dwordx4 v[92:95], v[108:109], off offset:144 nt
	v_mul_f32_e32 v99, v99, v99
	v_mul_f32_e32 v101, v101, v101
	v_mul_f32_e32 v103, v103, v103
	v_mul_f32_e32 v105, v105, v105
	v_fmac_f32_e32 v99, v98, v98
	v_fmac_f32_e32 v101, v100, v100
	v_fmac_f32_e32 v103, v102, v102
	v_fmac_f32_e32 v105, v104, v104
	v_add_f32_e32 v98, v99, v101
	v_add_f32_e32 v99, v103, v105
	v_add_f32_e32 v98, v98, v99
	s_waitcnt vmcnt(1)
	v_pk_add_f32 v[86:87], v[86:87], v[90:91]
	v_pk_add_f32 v[84:85], v[84:85], v[88:89]
	s_waitcnt vmcnt(0)
	v_pk_add_f32 v[88:89], v[82:83], v[94:95]
	v_pk_add_f32 v[90:91], v[80:81], v[92:93]
	v_mul_f32_e32 v80, v85, v85
	v_mul_f32_e32 v81, v87, v87
	v_mul_f32_e32 v82, v91, v91
	v_mul_f32_e32 v83, v89, v89
	v_fmac_f32_e32 v80, v84, v84
	v_fmac_f32_e32 v81, v86, v86
	v_fmac_f32_e32 v82, v90, v90
	v_fmac_f32_e32 v83, v88, v88
	v_add_f32_e32 v80, v80, v81
	v_add_f32_e32 v81, v82, v83
	v_add_f32_e32 v80, v80, v81
	v_add_f32_e32 v80, v98, v80
	ds_bpermute_b32 v81, v193, v80
	v_cvt_pk_bf16_f32 v82, v84, v85
	v_cvt_pk_bf16_f32 v83, v86, v87
	v_cvt_pk_bf16_f32 v84, v90, v91
	v_cvt_pk_bf16_f32 v85, v88, v89
	s_waitcnt lgkmcnt(0)
	v_add_f32_e32 v80, v80, v81
	ds_bpermute_b32 v81, v194, v80
	global_store_dwordx4 v[106:107], v[82:85], off offset:64 sc1
	s_and_saveexec_b64 s[46:47], vcc
	s_cbranch_execz .LBB0_391
	v_lshlrev_b64 v[82:83], 6, v[96:97]
	v_lshl_add_u64 v[82:83], s[6:7], 0, v[82:83]
	v_lshl_add_u64 v[82:83], s[44:45], 2, v[82:83]
	s_lshl_b32 s20, s29, 2
	v_lshl_add_u64 v[82:83], v[82:83], 0, s[20:21]
	s_waitcnt lgkmcnt(0)
	v_add_f32_e32 v80, v80, v81
	global_store_dword v[82:83], v80, off
.LBB0_391:
	s_or_b64 exec, exec, s[46:47]
	v_or_b32_e32 v80, 48, v142
	s_waitcnt lgkmcnt(0)
	v_ashrrev_i32_e32 v81, 31, v80
	v_lshlrev_b64 v[82:83], 10, v[80:81]
	v_lshl_add_u64 v[90:91], v[82:83], 0, v[140:141]
	v_lshl_add_u64 v[92:93], v[90:91], 2, s[12:13]
	global_load_dwordx4 v[82:85], v[92:93], off nt
	global_load_dwordx4 v[86:89], v[92:93], off offset:16 nt
	v_lshl_add_u64 v[90:91], v[90:91], 1, s[16:17]
	s_waitcnt vmcnt(1)
	v_pk_add_f32 v[84:85], v[78:79], v[84:85]
	v_pk_add_f32 v[82:83], v[76:77], v[82:83]
	s_waitcnt vmcnt(0)
	v_pk_add_f32 v[88:89], v[74:75], v[88:89]
	v_pk_add_f32 v[86:87], v[72:73], v[86:87]
	v_cvt_pk_bf16_f32 v72, v82, v83
	v_cvt_pk_bf16_f32 v73, v84, v85
	v_cvt_pk_bf16_f32 v74, v86, v87
	v_cvt_pk_bf16_f32 v75, v88, v89
	global_store_dwordx4 v[90:91], v[72:75], off sc1
	global_load_dwordx4 v[72:75], v[92:93], off offset:128 nt
	s_nop 0
	global_load_dwordx4 v[76:79], v[92:93], off offset:144 nt
	v_mul_f32_e32 v83, v83, v83
	v_mul_f32_e32 v85, v85, v85
	v_mul_f32_e32 v87, v87, v87
	v_mul_f32_e32 v89, v89, v89
	v_fmac_f32_e32 v83, v82, v82
	v_fmac_f32_e32 v85, v84, v84
	v_fmac_f32_e32 v87, v86, v86
	v_fmac_f32_e32 v89, v88, v88
	v_add_f32_e32 v82, v83, v85
	v_add_f32_e32 v83, v87, v89
	v_add_f32_e32 v82, v82, v83
	s_waitcnt vmcnt(1)
	v_pk_add_f32 v[70:71], v[70:71], v[74:75]
	v_pk_add_f32 v[68:69], v[68:69], v[72:73]
	s_waitcnt vmcnt(0)
	v_pk_add_f32 v[72:73], v[66:67], v[78:79]
	v_pk_add_f32 v[74:75], v[64:65], v[76:77]
	v_mul_f32_e32 v64, v69, v69
	v_mul_f32_e32 v65, v71, v71
	v_mul_f32_e32 v66, v75, v75
	v_mul_f32_e32 v67, v73, v73
	v_fmac_f32_e32 v64, v68, v68
	v_fmac_f32_e32 v65, v70, v70
	v_fmac_f32_e32 v66, v74, v74
	v_fmac_f32_e32 v67, v72, v72
	v_add_f32_e32 v64, v64, v65
	v_add_f32_e32 v65, v66, v67
	v_add_f32_e32 v64, v64, v65
	v_add_f32_e32 v64, v82, v64
	ds_bpermute_b32 v65, v193, v64
	v_cvt_pk_bf16_f32 v66, v68, v69
	v_cvt_pk_bf16_f32 v67, v70, v71
	v_cvt_pk_bf16_f32 v68, v74, v75
	v_cvt_pk_bf16_f32 v69, v72, v73
	s_waitcnt lgkmcnt(0)
	v_add_f32_e32 v64, v64, v65
	ds_bpermute_b32 v65, v194, v64
	global_store_dwordx4 v[90:91], v[66:69], off offset:64 sc1
	s_and_saveexec_b64 s[46:47], vcc
	s_cbranch_execz .LBB0_393
	v_lshlrev_b64 v[66:67], 6, v[80:81]
	v_lshl_add_u64 v[66:67], s[6:7], 0, v[66:67]
	v_lshl_add_u64 v[66:67], s[44:45], 2, v[66:67]
	s_lshl_b32 s20, s29, 2
	v_lshl_add_u64 v[66:67], v[66:67], 0, s[20:21]
	s_waitcnt lgkmcnt(0)
	v_add_f32_e32 v64, v64, v65
	global_store_dword v[66:67], v64, off
.LBB0_393:
	s_or_b64 exec, exec, s[46:47]
	v_add_u32_e32 v64, 0x80, v142
	s_waitcnt lgkmcnt(0)
	v_ashrrev_i32_e32 v65, 31, v64
	v_lshlrev_b64 v[66:67], 10, v[64:65]
	v_lshl_add_u64 v[74:75], v[66:67], 0, v[140:141]
	v_lshl_add_u64 v[76:77], v[74:75], 2, s[12:13]
	global_load_dwordx4 v[66:69], v[76:77], off nt
	global_load_dwordx4 v[70:73], v[76:77], off offset:16 nt
	v_lshl_add_u64 v[74:75], v[74:75], 1, s[16:17]
	s_waitcnt vmcnt(1)
	v_pk_add_f32 v[68:69], v[62:63], v[68:69]
	v_pk_add_f32 v[66:67], v[60:61], v[66:67]
	s_waitcnt vmcnt(0)
	v_pk_add_f32 v[72:73], v[58:59], v[72:73]
	v_pk_add_f32 v[70:71], v[56:57], v[70:71]
	v_cvt_pk_bf16_f32 v56, v66, v67
	v_cvt_pk_bf16_f32 v57, v68, v69
	v_cvt_pk_bf16_f32 v58, v70, v71
	v_cvt_pk_bf16_f32 v59, v72, v73
	global_store_dwordx4 v[74:75], v[56:59], off sc1
	global_load_dwordx4 v[56:59], v[76:77], off offset:128 nt
	s_nop 0
	global_load_dwordx4 v[60:63], v[76:77], off offset:144 nt
	v_mul_f32_e32 v67, v67, v67
	v_mul_f32_e32 v69, v69, v69
	v_mul_f32_e32 v71, v71, v71
	v_mul_f32_e32 v73, v73, v73
	v_fmac_f32_e32 v67, v66, v66
	v_fmac_f32_e32 v69, v68, v68
	v_fmac_f32_e32 v71, v70, v70
	v_fmac_f32_e32 v73, v72, v72
	v_add_f32_e32 v66, v67, v69
	v_add_f32_e32 v67, v71, v73
	v_add_f32_e32 v66, v66, v67
	s_waitcnt vmcnt(1)
	v_pk_add_f32 v[54:55], v[54:55], v[58:59]
	v_pk_add_f32 v[52:53], v[52:53], v[56:57]
	s_waitcnt vmcnt(0)
	v_pk_add_f32 v[56:57], v[50:51], v[62:63]
	v_pk_add_f32 v[58:59], v[48:49], v[60:61]
	v_mul_f32_e32 v48, v53, v53
	v_mul_f32_e32 v49, v55, v55
	v_mul_f32_e32 v50, v59, v59
	v_mul_f32_e32 v51, v57, v57
	v_fmac_f32_e32 v48, v52, v52
	v_fmac_f32_e32 v49, v54, v54
	v_fmac_f32_e32 v50, v58, v58
	v_fmac_f32_e32 v51, v56, v56
	v_add_f32_e32 v48, v48, v49
	v_add_f32_e32 v49, v50, v51
	v_add_f32_e32 v48, v48, v49
	v_add_f32_e32 v48, v66, v48
	ds_bpermute_b32 v49, v193, v48
	v_cvt_pk_bf16_f32 v50, v52, v53
	v_cvt_pk_bf16_f32 v51, v54, v55
	v_cvt_pk_bf16_f32 v52, v58, v59
	v_cvt_pk_bf16_f32 v53, v56, v57
	s_waitcnt lgkmcnt(0)
	v_add_f32_e32 v48, v48, v49
	ds_bpermute_b32 v49, v194, v48
	global_store_dwordx4 v[74:75], v[50:53], off offset:64 sc1
	s_and_saveexec_b64 s[46:47], vcc
	s_cbranch_execz .LBB0_395
	v_lshlrev_b64 v[50:51], 6, v[64:65]
	v_lshl_add_u64 v[50:51], s[6:7], 0, v[50:51]
	v_lshl_add_u64 v[50:51], s[44:45], 2, v[50:51]
	s_lshl_b32 s20, s29, 2
	v_lshl_add_u64 v[50:51], v[50:51], 0, s[20:21]
	s_waitcnt lgkmcnt(0)
	v_add_f32_e32 v48, v48, v49
	global_store_dword v[50:51], v48, off
.LBB0_395:
	s_or_b64 exec, exec, s[46:47]
	v_add_u32_e32 v48, 0x90, v142
	s_waitcnt lgkmcnt(0)
	v_ashrrev_i32_e32 v49, 31, v48
	v_lshlrev_b64 v[50:51], 10, v[48:49]
	v_lshl_add_u64 v[58:59], v[50:51], 0, v[140:141]
	v_lshl_add_u64 v[60:61], v[58:59], 2, s[12:13]
	global_load_dwordx4 v[50:53], v[60:61], off nt
	global_load_dwordx4 v[54:57], v[60:61], off offset:16 nt
	v_lshl_add_u64 v[58:59], v[58:59], 1, s[16:17]
	s_waitcnt vmcnt(1)
	v_pk_add_f32 v[52:53], v[46:47], v[52:53]
	v_pk_add_f32 v[50:51], v[44:45], v[50:51]
	s_waitcnt vmcnt(0)
	v_pk_add_f32 v[56:57], v[42:43], v[56:57]
	v_pk_add_f32 v[54:55], v[40:41], v[54:55]
	v_cvt_pk_bf16_f32 v40, v50, v51
	v_cvt_pk_bf16_f32 v41, v52, v53
	v_cvt_pk_bf16_f32 v42, v54, v55
	v_cvt_pk_bf16_f32 v43, v56, v57
	global_store_dwordx4 v[58:59], v[40:43], off sc1
	global_load_dwordx4 v[40:43], v[60:61], off offset:128 nt
	s_nop 0
	global_load_dwordx4 v[44:47], v[60:61], off offset:144 nt
	v_mul_f32_e32 v51, v51, v51
	v_mul_f32_e32 v53, v53, v53
	v_mul_f32_e32 v55, v55, v55
	v_mul_f32_e32 v57, v57, v57
	v_fmac_f32_e32 v51, v50, v50
	v_fmac_f32_e32 v53, v52, v52
	v_fmac_f32_e32 v55, v54, v54
	v_fmac_f32_e32 v57, v56, v56
	v_add_f32_e32 v50, v51, v53
	v_add_f32_e32 v51, v55, v57
	v_add_f32_e32 v50, v50, v51
	s_waitcnt vmcnt(1)
	v_pk_add_f32 v[38:39], v[38:39], v[42:43]
	v_pk_add_f32 v[36:37], v[36:37], v[40:41]
	s_waitcnt vmcnt(0)
	v_pk_add_f32 v[40:41], v[34:35], v[46:47]
	v_pk_add_f32 v[42:43], v[32:33], v[44:45]
	v_mul_f32_e32 v32, v37, v37
	v_mul_f32_e32 v33, v39, v39
	v_mul_f32_e32 v34, v43, v43
	v_mul_f32_e32 v35, v41, v41
	v_fmac_f32_e32 v32, v36, v36
	v_fmac_f32_e32 v33, v38, v38
	v_fmac_f32_e32 v34, v42, v42
	v_fmac_f32_e32 v35, v40, v40
	v_add_f32_e32 v32, v32, v33
	v_add_f32_e32 v33, v34, v35
	v_add_f32_e32 v32, v32, v33
	v_add_f32_e32 v32, v50, v32
	ds_bpermute_b32 v33, v193, v32
	v_cvt_pk_bf16_f32 v34, v36, v37
	v_cvt_pk_bf16_f32 v35, v38, v39
	v_cvt_pk_bf16_f32 v36, v42, v43
	v_cvt_pk_bf16_f32 v37, v40, v41
	s_waitcnt lgkmcnt(0)
	v_add_f32_e32 v32, v32, v33
	ds_bpermute_b32 v33, v194, v32
	global_store_dwordx4 v[58:59], v[34:37], off offset:64 sc1
	s_and_saveexec_b64 s[46:47], vcc
	s_cbranch_execz .LBB0_397
	v_lshlrev_b64 v[34:35], 6, v[48:49]
	v_lshl_add_u64 v[34:35], s[6:7], 0, v[34:35]
	v_lshl_add_u64 v[34:35], s[44:45], 2, v[34:35]
	s_lshl_b32 s20, s29, 2
	v_lshl_add_u64 v[34:35], v[34:35], 0, s[20:21]
	s_waitcnt lgkmcnt(0)
	v_add_f32_e32 v32, v32, v33
	global_store_dword v[34:35], v32, off
.LBB0_397:
	s_or_b64 exec, exec, s[46:47]
	v_add_u32_e32 v32, 0xa0, v142
	s_waitcnt lgkmcnt(0)
	v_ashrrev_i32_e32 v33, 31, v32
	v_lshlrev_b64 v[34:35], 10, v[32:33]
	v_lshl_add_u64 v[42:43], v[34:35], 0, v[140:141]
	v_lshl_add_u64 v[44:45], v[42:43], 2, s[12:13]
	global_load_dwordx4 v[34:37], v[44:45], off nt
	global_load_dwordx4 v[38:41], v[44:45], off offset:16 nt
	v_lshl_add_u64 v[42:43], v[42:43], 1, s[16:17]
	s_waitcnt vmcnt(1)
	v_pk_add_f32 v[36:37], v[30:31], v[36:37]
	v_pk_add_f32 v[34:35], v[28:29], v[34:35]
	s_waitcnt vmcnt(0)
	v_pk_add_f32 v[40:41], v[26:27], v[40:41]
	v_pk_add_f32 v[38:39], v[24:25], v[38:39]
	v_cvt_pk_bf16_f32 v24, v34, v35
	v_cvt_pk_bf16_f32 v25, v36, v37
	v_cvt_pk_bf16_f32 v26, v38, v39
	v_cvt_pk_bf16_f32 v27, v40, v41
	global_store_dwordx4 v[42:43], v[24:27], off sc1
	global_load_dwordx4 v[24:27], v[44:45], off offset:128 nt
	s_nop 0
	global_load_dwordx4 v[28:31], v[44:45], off offset:144 nt
	v_mul_f32_e32 v35, v35, v35
	v_mul_f32_e32 v37, v37, v37
	v_mul_f32_e32 v39, v39, v39
	v_mul_f32_e32 v41, v41, v41
	v_fmac_f32_e32 v35, v34, v34
	v_fmac_f32_e32 v37, v36, v36
	v_fmac_f32_e32 v39, v38, v38
	v_fmac_f32_e32 v41, v40, v40
	v_add_f32_e32 v34, v35, v37
	v_add_f32_e32 v35, v39, v41
	v_add_f32_e32 v34, v34, v35
	s_waitcnt vmcnt(1)
	v_pk_add_f32 v[22:23], v[22:23], v[26:27]
	v_pk_add_f32 v[20:21], v[20:21], v[24:25]
	s_waitcnt vmcnt(0)
	v_pk_add_f32 v[24:25], v[18:19], v[30:31]
	v_pk_add_f32 v[26:27], v[16:17], v[28:29]
	v_mul_f32_e32 v16, v21, v21
	v_mul_f32_e32 v17, v23, v23
	v_mul_f32_e32 v18, v27, v27
	v_mul_f32_e32 v19, v25, v25
	v_fmac_f32_e32 v16, v20, v20
	v_fmac_f32_e32 v17, v22, v22
	v_fmac_f32_e32 v18, v26, v26
	v_fmac_f32_e32 v19, v24, v24
	v_add_f32_e32 v16, v16, v17
	v_add_f32_e32 v17, v18, v19
	v_add_f32_e32 v16, v16, v17
	v_add_f32_e32 v16, v34, v16
	ds_bpermute_b32 v17, v193, v16
	v_cvt_pk_bf16_f32 v18, v20, v21
	v_cvt_pk_bf16_f32 v19, v22, v23
	v_cvt_pk_bf16_f32 v20, v26, v27
	v_cvt_pk_bf16_f32 v21, v24, v25
	s_waitcnt lgkmcnt(0)
	v_add_f32_e32 v16, v16, v17
	ds_bpermute_b32 v17, v194, v16
	global_store_dwordx4 v[42:43], v[18:21], off offset:64 sc1
	s_and_saveexec_b64 s[46:47], vcc
	s_cbranch_execz .LBB0_399
	v_lshlrev_b64 v[18:19], 6, v[32:33]
	v_lshl_add_u64 v[18:19], s[6:7], 0, v[18:19]
	v_lshl_add_u64 v[18:19], s[44:45], 2, v[18:19]
	s_lshl_b32 s20, s29, 2
	v_lshl_add_u64 v[18:19], v[18:19], 0, s[20:21]
	s_waitcnt lgkmcnt(0)
	v_add_f32_e32 v16, v16, v17
	global_store_dword v[18:19], v16, off
.LBB0_399:
	s_or_b64 exec, exec, s[46:47]
	v_add_u32_e32 v16, 0xb0, v142
	s_waitcnt lgkmcnt(0)
	v_ashrrev_i32_e32 v17, 31, v16
	v_lshlrev_b64 v[18:19], 10, v[16:17]
	v_lshl_add_u64 v[26:27], v[18:19], 0, v[140:141]
	v_lshl_add_u64 v[28:29], v[26:27], 2, s[12:13]
	global_load_dwordx4 v[18:21], v[28:29], off nt
	global_load_dwordx4 v[22:25], v[28:29], off offset:16 nt
	v_lshl_add_u64 v[26:27], v[26:27], 1, s[16:17]
	s_waitcnt vmcnt(1)
	v_pk_add_f32 v[20:21], v[14:15], v[20:21]
	v_pk_add_f32 v[18:19], v[12:13], v[18:19]
	s_waitcnt vmcnt(0)
	v_pk_add_f32 v[24:25], v[10:11], v[24:25]
	v_pk_add_f32 v[22:23], v[8:9], v[22:23]
	v_cvt_pk_bf16_f32 v8, v18, v19
	v_cvt_pk_bf16_f32 v9, v20, v21
	v_cvt_pk_bf16_f32 v10, v22, v23
	v_cvt_pk_bf16_f32 v11, v24, v25
	global_store_dwordx4 v[26:27], v[8:11], off sc1
	global_load_dwordx4 v[8:11], v[28:29], off offset:128 nt
	s_nop 0
	global_load_dwordx4 v[12:15], v[28:29], off offset:144 nt
	v_mul_f32_e32 v19, v19, v19
	v_mul_f32_e32 v21, v21, v21
	v_mul_f32_e32 v23, v23, v23
	v_mul_f32_e32 v25, v25, v25
	v_fmac_f32_e32 v19, v18, v18
	v_fmac_f32_e32 v21, v20, v20
	v_fmac_f32_e32 v23, v22, v22
	v_fmac_f32_e32 v25, v24, v24
	v_add_f32_e32 v18, v19, v21
	v_add_f32_e32 v19, v23, v25
	v_add_f32_e32 v18, v18, v19
	s_waitcnt vmcnt(1)
	v_pk_add_f32 v[6:7], v[6:7], v[10:11]
	v_pk_add_f32 v[4:5], v[4:5], v[8:9]
	s_waitcnt vmcnt(0)
	v_pk_add_f32 v[8:9], v[2:3], v[14:15]
	v_pk_add_f32 v[10:11], v[0:1], v[12:13]
	v_mul_f32_e32 v0, v5, v5
	v_mul_f32_e32 v1, v7, v7
	v_mul_f32_e32 v2, v11, v11
	v_mul_f32_e32 v3, v9, v9
	v_fmac_f32_e32 v0, v4, v4
	v_fmac_f32_e32 v1, v6, v6
	v_fmac_f32_e32 v2, v10, v10
	v_fmac_f32_e32 v3, v8, v8
	v_add_f32_e32 v0, v0, v1
	v_add_f32_e32 v1, v2, v3
	v_add_f32_e32 v0, v0, v1
	v_add_f32_e32 v0, v18, v0
	ds_bpermute_b32 v1, v193, v0
	v_cvt_pk_bf16_f32 v2, v4, v5
	v_cvt_pk_bf16_f32 v3, v6, v7
	v_cvt_pk_bf16_f32 v4, v10, v11
	v_cvt_pk_bf16_f32 v5, v8, v9
	s_waitcnt lgkmcnt(0)
	v_add_f32_e32 v0, v0, v1
	ds_bpermute_b32 v1, v194, v0
	global_store_dwordx4 v[26:27], v[2:5], off offset:64 sc1
	s_and_saveexec_b64 s[46:47], vcc
	s_cbranch_execz .LBB0_401
	v_lshlrev_b64 v[2:3], 6, v[16:17]
	v_lshl_add_u64 v[2:3], s[6:7], 0, v[2:3]
	v_lshl_add_u64 v[2:3], s[44:45], 2, v[2:3]
	s_lshl_b32 s20, s29, 2
	v_lshl_add_u64 v[2:3], v[2:3], 0, s[20:21]
	s_waitcnt lgkmcnt(0)
	v_add_f32_e32 v0, v0, v1
	global_store_dword v[2:3], v0, off
